# mix2 gating epilogue: 8 gate + 8 y_intra loads per head pass hoisted ahead of the compute steps with counted vmcnt; on top of candidate B
# speedup vs baseline: 1.0118x; 1.0059x over previous
.LBB0_42:
	v_lshl_or_b32 v2, v137, 6, v133
	v_ashrrev_i32_e32 v3, 31, v2
	v_lshlrev_b64 v[26:27], 1, v[2:3]
	v_lshlrev_b64 v[28:29], 2, v[2:3]
	v_lshl_add_u64 v[238:239], v[86:87], 0, v[26:27]
	v_lshl_add_u64 v[240:241], v[88:89], 0, v[26:27]
	v_lshl_add_u64 v[242:243], v[84:85], 0, v[28:29]
	v_lshl_add_u64 v[244:245], v[76:77], 0, v[28:29]
	global_load_dwordx2 v[222:223], v[238:239], off
	global_load_dwordx4 v[176:179], v[242:243], off
	global_load_dwordx2 v[224:225], v[238:239], off offset:32
	global_load_dwordx4 v[180:183], v[242:243], off offset:64
	global_load_dwordx2 v[226:227], v[238:239], off offset:64
	global_load_dwordx4 v[184:187], v[242:243], off offset:128
	global_load_dwordx2 v[228:229], v[238:239], off offset:96
	global_load_dwordx4 v[188:191], v[242:243], off offset:192
	global_load_dwordx2 v[230:231], v[240:241], off
	global_load_dwordx4 v[192:195], v[244:245], off
	global_load_dwordx2 v[232:233], v[240:241], off offset:32
	global_load_dwordx4 v[196:199], v[244:245], off offset:64
	global_load_dwordx2 v[234:235], v[240:241], off offset:64
	global_load_dwordx4 v[200:203], v[244:245], off offset:128
	global_load_dwordx2 v[236:237], v[240:241], off offset:96
	global_load_dwordx4 v[204:207], v[244:245], off offset:192
	v_lshl_add_u64 v[4:5], v[86:87], 0, v[26:27]
	v_lshl_add_u64 v[0:1], v[84:85], 0, v[28:29]
	s_nop 0
	v_lshlrev_b32_e32 v32, 1, v2
	s_mov_b32 s0, 1
	s_waitcnt vmcnt(15)
	v_cvt_f32_f16_sdwa v3, v222 dst_sel:DWORD dst_unused:UNUSED_PAD src0_sel:WORD_1
	v_cvt_f32_f16_e32 v8, v222
	s_waitcnt vmcnt(14)
	v_pk_add_f32 v[4:5], v[124:125], v[176:177]
	v_pk_add_f32 v[6:7], v[122:123], v[178:179]
	v_mul_f32_e32 v11, 0xbfb8aa3b, v3
	v_mul_f32_e32 v10, 0xbfb8aa3b, v8
	v_exp_f32_e32 v10, v10
	v_exp_f32_e32 v11, v11
	s_nop 0
	v_pk_add_f32 v[10:11], v[10:11], 1.0 op_sel_hi:[1,0]
	s_nop 0
	v_div_scale_f32 v12, s[4:5], v11, v11, v3
	v_rcp_f32_e32 v13, v12
	s_nop 0
	v_fma_f32 v14, -v12, v13, 1.0
	v_fmac_f32_e32 v13, v14, v13
	v_div_scale_f32 v14, vcc, v3, v11, v3
	v_mul_f32_e32 v15, v14, v13
	v_fma_f32 v16, -v12, v15, v14
	v_fmac_f32_e32 v15, v16, v13
	v_fma_f32 v12, -v12, v15, v14
	v_div_fmas_f32 v12, v12, v13, v15
	v_div_fixup_f32 v11, v12, v11, v3
	v_div_scale_f32 v3, s[4:5], v10, v10, v8
	v_rcp_f32_e32 v12, v3
	s_nop 0
	v_fma_f32 v13, -v3, v12, 1.0
	v_fmac_f32_e32 v12, v13, v12
	v_div_scale_f32 v13, vcc, v8, v10, v8
	v_mul_f32_e32 v14, v13, v12
	v_fma_f32 v15, -v3, v14, v13
	v_fmac_f32_e32 v14, v15, v12
	v_fma_f32 v3, -v3, v14, v13
	v_div_fmas_f32 v3, v3, v12, v14
	v_div_fixup_f32 v10, v3, v10, v8
	v_pk_mul_f32 v[4:5], v[4:5], v[10:11]
	v_cvt_f32_f16_sdwa v3, v223 dst_sel:DWORD dst_unused:UNUSED_PAD src0_sel:WORD_1
	v_cvt_f32_f16_e32 v10, v223
	v_cvt_pk_f16_f32 v12, v4, v5
	v_mul_f32_e32 v9, 0xbfb8aa3b, v3
	v_mul_f32_e32 v8, 0xbfb8aa3b, v10
	v_exp_f32_e32 v8, v8
	v_exp_f32_e32 v9, v9
	s_nop 0
	v_pk_add_f32 v[8:9], v[8:9], 1.0 op_sel_hi:[1,0]
	s_nop 0
	v_div_scale_f32 v11, s[4:5], v9, v9, v3
	v_rcp_f32_e32 v13, v11
	s_nop 0
	v_fma_f32 v14, -v11, v13, 1.0
	v_fmac_f32_e32 v13, v14, v13
	v_div_scale_f32 v14, vcc, v3, v9, v3
	v_mul_f32_e32 v15, v14, v13
	v_fma_f32 v16, -v11, v15, v14
	v_fmac_f32_e32 v15, v16, v13
	v_fma_f32 v11, -v11, v15, v14
	v_div_fmas_f32 v11, v11, v13, v15
	v_div_fixup_f32 v9, v11, v9, v3
	v_div_scale_f32 v3, s[4:5], v8, v8, v10
	v_rcp_f32_e32 v11, v3
	s_nop 0
	v_fma_f32 v13, -v3, v11, 1.0
	v_fmac_f32_e32 v11, v13, v11
	v_div_scale_f32 v13, vcc, v10, v8, v10
	v_mul_f32_e32 v14, v13, v11
	v_fma_f32 v15, -v3, v14, v13
	v_fmac_f32_e32 v14, v15, v11
	v_fma_f32 v3, -v3, v14, v13
	v_div_fmas_f32 v3, v3, v11, v14
	v_div_fixup_f32 v8, v3, v8, v10
	v_pk_mul_f32 v[6:7], v[6:7], v[8:9]
	v_or_b32_e32 v8, 16, v2
	v_ashrrev_i32_e32 v9, 31, v8
	v_lshlrev_b64 v[22:23], 1, v[8:9]
	v_lshl_add_u64 v[8:9], v[86:87], 0, v[22:23]
	s_nop 0
	v_add_u32_e32 v3, v81, v32
	v_cvt_pk_f16_f32 v13, v6, v7
	v_add_u32_e32 v33, 0x4000, v3
	v_lshl_add_u64 v[22:23], v[88:89], 0, v[22:23]
	v_add_u32_e32 v32, v79, v32
	s_waitcnt vmcnt(13)
	v_cvt_f32_f16_sdwa v18, v224 dst_sel:DWORD dst_unused:UNUSED_PAD src0_sel:WORD_1
	v_cvt_f32_f16_e32 v14, v224
	s_waitcnt vmcnt(12)
	v_pk_add_f32 v[8:9], v[120:121], v[180:181]
	v_pk_add_f32 v[10:11], v[118:119], v[182:183]
	v_mul_f32_e32 v17, 0xbfb8aa3b, v18
	v_mul_f32_e32 v16, 0xbfb8aa3b, v14
	v_exp_f32_e32 v16, v16
	v_exp_f32_e32 v17, v17
	s_nop 0
	v_pk_add_f32 v[16:17], v[16:17], 1.0 op_sel_hi:[1,0]
	s_nop 0
	v_div_scale_f32 v19, s[4:5], v17, v17, v18
	v_rcp_f32_e32 v20, v19
	s_nop 0
	v_fma_f32 v21, -v19, v20, 1.0
	v_fmac_f32_e32 v20, v21, v20
	v_div_scale_f32 v21, vcc, v18, v17, v18
	v_mul_f32_e32 v24, v21, v20
	v_fma_f32 v25, -v19, v24, v21
	v_fmac_f32_e32 v24, v25, v20
	v_fma_f32 v19, -v19, v24, v21
	v_div_fmas_f32 v19, v19, v20, v24
	v_div_fixup_f32 v17, v19, v17, v18
	v_div_scale_f32 v18, s[4:5], v16, v16, v14
	v_rcp_f32_e32 v19, v18
	s_nop 0
	v_fma_f32 v20, -v18, v19, 1.0
	v_fmac_f32_e32 v19, v20, v19
	v_div_scale_f32 v20, vcc, v14, v16, v14
	v_mul_f32_e32 v21, v20, v19
	v_fma_f32 v24, -v18, v21, v20
	v_fmac_f32_e32 v21, v24, v19
	v_fma_f32 v18, -v18, v21, v20
	v_div_fmas_f32 v18, v18, v19, v21
	v_div_fixup_f32 v16, v18, v16, v14
	v_cvt_f32_f16_sdwa v18, v225 dst_sel:DWORD dst_unused:UNUSED_PAD src0_sel:WORD_1
	v_cvt_f32_f16_e32 v15, v225
	v_pk_mul_f32 v[8:9], v[8:9], v[16:17]
	v_mul_f32_e32 v17, 0xbfb8aa3b, v18
	v_mul_f32_e32 v16, 0xbfb8aa3b, v15
	v_exp_f32_e32 v16, v16
	v_exp_f32_e32 v17, v17
	v_cvt_pk_f16_f32 v14, v8, v9
	v_pk_add_f32 v[16:17], v[16:17], 1.0 op_sel_hi:[1,0]
	s_nop 0
	v_div_scale_f32 v19, s[4:5], v17, v17, v18
	v_rcp_f32_e32 v20, v19
	s_nop 0
	v_fma_f32 v21, -v19, v20, 1.0
	v_fmac_f32_e32 v20, v21, v20
	v_div_scale_f32 v21, vcc, v18, v17, v18
	v_mul_f32_e32 v24, v21, v20
	v_fma_f32 v25, -v19, v24, v21
	v_fmac_f32_e32 v24, v25, v20
	v_fma_f32 v19, -v19, v24, v21
	v_div_fmas_f32 v19, v19, v20, v24
	v_div_fixup_f32 v17, v19, v17, v18
	v_div_scale_f32 v18, s[4:5], v16, v16, v15
	v_rcp_f32_e32 v19, v18
	s_nop 0
	v_fma_f32 v20, -v18, v19, 1.0
	v_fmac_f32_e32 v19, v20, v19
	v_div_scale_f32 v20, vcc, v15, v16, v15
	v_mul_f32_e32 v21, v20, v19
	v_fma_f32 v24, -v18, v21, v20
	v_fmac_f32_e32 v21, v24, v19
	v_fma_f32 v18, -v18, v21, v20
	v_div_fmas_f32 v18, v18, v19, v21
	v_div_fixup_f32 v16, v18, v16, v15
	v_pk_mul_f32 v[10:11], v[10:11], v[16:17]
	s_nop 0
	v_cvt_pk_f16_f32 v15, v10, v11
	ds_write2_b64 v33, v[12:13], v[14:15] offset0:64 offset1:68
	v_or_b32_e32 v12, 32, v2
	v_ashrrev_i32_e32 v13, 31, v12
	v_lshlrev_b64 v[20:21], 1, v[12:13]
	v_lshl_add_u64 v[12:13], v[86:87], 0, v[20:21]
	s_nop 0
	v_or_b32_e32 v2, 48, v2
	s_waitcnt vmcnt(11)
	v_cvt_f32_f16_sdwa v3, v226 dst_sel:DWORD dst_unused:UNUSED_PAD src0_sel:WORD_1
	v_cvt_f32_f16_e32 v16, v226
	s_waitcnt vmcnt(10)
	v_pk_add_f32 v[12:13], v[116:117], v[184:185]
	v_pk_add_f32 v[14:15], v[114:115], v[186:187]
	v_mul_f32_e32 v19, 0xbfb8aa3b, v3
	v_mul_f32_e32 v18, 0xbfb8aa3b, v16
	v_exp_f32_e32 v18, v18
	v_exp_f32_e32 v19, v19
	s_nop 0
	v_pk_add_f32 v[18:19], v[18:19], 1.0 op_sel_hi:[1,0]
	s_nop 0
	v_div_scale_f32 v24, s[4:5], v19, v19, v3
	v_rcp_f32_e32 v25, v24
	s_nop 0
	v_fma_f32 v30, -v24, v25, 1.0
	v_fmac_f32_e32 v25, v30, v25
	v_div_scale_f32 v30, vcc, v3, v19, v3
	v_mul_f32_e32 v31, v30, v25
	v_fma_f32 v34, -v24, v31, v30
	v_fmac_f32_e32 v31, v34, v25
	v_fma_f32 v24, -v24, v31, v30
	v_div_fmas_f32 v24, v24, v25, v31
	v_div_fixup_f32 v19, v24, v19, v3
	v_div_scale_f32 v3, s[4:5], v18, v18, v16
	v_rcp_f32_e32 v24, v3
	s_nop 0
	v_fma_f32 v25, -v3, v24, 1.0
	v_fmac_f32_e32 v24, v25, v24
	v_div_scale_f32 v25, vcc, v16, v18, v16
	v_mul_f32_e32 v30, v25, v24
	v_fma_f32 v31, -v3, v30, v25
	v_fmac_f32_e32 v30, v31, v24
	v_fma_f32 v3, -v3, v30, v25
	v_div_fmas_f32 v3, v3, v24, v30
	v_div_fixup_f32 v18, v3, v18, v16
	v_pk_mul_f32 v[12:13], v[12:13], v[18:19]
	v_cvt_f32_f16_sdwa v3, v227 dst_sel:DWORD dst_unused:UNUSED_PAD src0_sel:WORD_1
	v_cvt_f32_f16_e32 v18, v227
	v_cvt_pk_f16_f32 v30, v12, v13
	v_mul_f32_e32 v17, 0xbfb8aa3b, v3
	v_mul_f32_e32 v16, 0xbfb8aa3b, v18
	v_exp_f32_e32 v16, v16
	v_exp_f32_e32 v17, v17
	s_nop 0
	v_pk_add_f32 v[16:17], v[16:17], 1.0 op_sel_hi:[1,0]
	s_nop 0
	v_div_scale_f32 v19, s[4:5], v17, v17, v3
	v_rcp_f32_e32 v24, v19
	s_nop 0
	v_fma_f32 v25, -v19, v24, 1.0
	v_fmac_f32_e32 v24, v25, v24
	v_div_scale_f32 v25, vcc, v3, v17, v3
	v_mul_f32_e32 v31, v25, v24
	v_fma_f32 v34, -v19, v31, v25
	v_fmac_f32_e32 v31, v34, v24
	v_fma_f32 v19, -v19, v31, v25
	v_div_fmas_f32 v19, v19, v24, v31
	v_div_fixup_f32 v17, v19, v17, v3
	v_div_scale_f32 v3, s[4:5], v16, v16, v18
	v_rcp_f32_e32 v19, v3
	s_nop 0
	v_fma_f32 v24, -v3, v19, 1.0
	v_fmac_f32_e32 v19, v24, v19
	v_div_scale_f32 v24, vcc, v18, v16, v18
	v_mul_f32_e32 v25, v24, v19
	v_fma_f32 v31, -v3, v25, v24
	v_fmac_f32_e32 v25, v31, v19
	v_fma_f32 v3, -v3, v25, v24
	v_div_fmas_f32 v3, v3, v19, v25
	v_div_fixup_f32 v16, v3, v16, v18
	v_ashrrev_i32_e32 v3, 31, v2
	v_lshlrev_b64 v[24:25], 1, v[2:3]
	v_lshl_add_u64 v[2:3], v[86:87], 0, v[24:25]
	s_nop 0
	v_pk_mul_f32 v[14:15], v[14:15], v[16:17]
	s_waitcnt vmcnt(9)
	v_cvt_f32_f16_sdwa v34, v228 dst_sel:DWORD dst_unused:UNUSED_PAD src0_sel:WORD_1
	v_cvt_f32_f16_e32 v18, v228
	s_waitcnt vmcnt(8)
	v_pk_add_f32 v[0:1], v[112:113], v[188:189]
	v_pk_add_f32 v[2:3], v[110:111], v[190:191]
	v_mul_f32_e32 v17, 0xbfb8aa3b, v34
	v_mul_f32_e32 v16, 0xbfb8aa3b, v18
	v_exp_f32_e32 v16, v16
	v_exp_f32_e32 v17, v17
	v_cvt_pk_f16_f32 v31, v14, v15
	v_pk_add_f32 v[16:17], v[16:17], 1.0 op_sel_hi:[1,0]
	s_nop 0
	v_div_scale_f32 v35, s[4:5], v17, v17, v34
	v_rcp_f32_e32 v36, v35
	s_nop 0
	v_fma_f32 v37, -v35, v36, 1.0
	v_fmac_f32_e32 v36, v37, v36
	v_div_scale_f32 v37, vcc, v34, v17, v34
	v_mul_f32_e32 v38, v37, v36
	v_fma_f32 v39, -v35, v38, v37
	v_fmac_f32_e32 v38, v39, v36
	v_fma_f32 v35, -v35, v38, v37
	v_div_fmas_f32 v35, v35, v36, v38
	v_div_fixup_f32 v17, v35, v17, v34
	v_div_scale_f32 v34, s[4:5], v16, v16, v18
	v_rcp_f32_e32 v35, v34
	s_nop 0
	v_fma_f32 v36, -v34, v35, 1.0
	v_fmac_f32_e32 v35, v36, v35
	v_div_scale_f32 v36, vcc, v18, v16, v18
	v_mul_f32_e32 v37, v36, v35
	v_fma_f32 v38, -v34, v37, v36
	v_fmac_f32_e32 v37, v38, v35
	v_fma_f32 v34, -v34, v37, v36
	v_div_fmas_f32 v34, v34, v35, v37
	v_div_fixup_f32 v16, v34, v16, v18
	v_pk_mul_f32 v[16:17], v[0:1], v[16:17]
	v_cvt_f32_f16_sdwa v1, v229 dst_sel:DWORD dst_unused:UNUSED_PAD src0_sel:WORD_1
	v_cvt_f32_f16_e32 v34, v229
	v_cvt_pk_f16_f32 v0, v16, v17
	v_mul_f32_e32 v19, 0xbfb8aa3b, v1
	v_mul_f32_e32 v18, 0xbfb8aa3b, v34
	v_exp_f32_e32 v18, v18
	v_exp_f32_e32 v19, v19
	s_nop 0
	v_pk_add_f32 v[18:19], v[18:19], 1.0 op_sel_hi:[1,0]
	s_nop 0
	v_div_scale_f32 v35, s[4:5], v19, v19, v1
	v_rcp_f32_e32 v36, v35
	s_nop 0
	v_fma_f32 v37, -v35, v36, 1.0
	v_fmac_f32_e32 v36, v37, v36
	v_div_scale_f32 v37, vcc, v1, v19, v1
	v_mul_f32_e32 v38, v37, v36
	v_fma_f32 v39, -v35, v38, v37
	v_fmac_f32_e32 v38, v39, v36
	v_fma_f32 v35, -v35, v38, v37
	v_div_fmas_f32 v35, v35, v36, v38
	v_div_fixup_f32 v19, v35, v19, v1
	v_div_scale_f32 v1, s[4:5], v18, v18, v34
	v_rcp_f32_e32 v35, v1
	s_nop 0
	v_fma_f32 v36, -v1, v35, 1.0
	v_fmac_f32_e32 v35, v36, v35
	v_div_scale_f32 v36, vcc, v34, v18, v34
	v_mul_f32_e32 v37, v36, v35
	v_fma_f32 v38, -v1, v37, v36
	v_fmac_f32_e32 v37, v38, v35
	v_fma_f32 v1, -v1, v37, v36
	v_div_fmas_f32 v1, v1, v35, v37
	v_div_fixup_f32 v18, v1, v18, v34
	v_pk_mul_f32 v[18:19], v[2:3], v[18:19]
	v_lshl_add_u64 v[2:3], v[88:89], 0, v[26:27]
	v_cvt_pk_f16_f32 v1, v18, v19
	ds_write2_b64 v33, v[30:31], v[0:1] offset0:72 offset1:76
	v_lshl_add_u64 v[0:1], v[76:77], 0, v[28:29]
	s_nop 0
	s_waitcnt vmcnt(7)
	v_cvt_f32_f16_sdwa v33, v230 dst_sel:DWORD dst_unused:UNUSED_PAD src0_sel:WORD_1
	v_cvt_f32_f16_e32 v2, v230
	s_waitcnt vmcnt(6)
	v_pk_add_f32 v[26:27], v[108:109], v[192:193]
	v_pk_add_f32 v[28:29], v[106:107], v[194:195]
	v_mul_f32_e32 v31, 0xbfb8aa3b, v33
	v_mul_f32_e32 v30, 0xbfb8aa3b, v2
	v_exp_f32_e32 v30, v30
	v_exp_f32_e32 v31, v31
	s_nop 0
	v_pk_add_f32 v[30:31], v[30:31], 1.0 op_sel_hi:[1,0]
	s_nop 0
	v_div_scale_f32 v34, s[4:5], v31, v31, v33
	v_rcp_f32_e32 v35, v34
	s_nop 0
	v_fma_f32 v36, -v34, v35, 1.0
	v_fmac_f32_e32 v35, v36, v35
	v_div_scale_f32 v36, vcc, v33, v31, v33
	v_mul_f32_e32 v37, v36, v35
	v_fma_f32 v38, -v34, v37, v36
	v_fmac_f32_e32 v37, v38, v35
	v_fma_f32 v34, -v34, v37, v36
	v_div_fmas_f32 v34, v34, v35, v37
	v_div_fixup_f32 v31, v34, v31, v33
	v_div_scale_f32 v33, s[4:5], v30, v30, v2
	v_rcp_f32_e32 v34, v33
	s_nop 0
	v_fma_f32 v35, -v33, v34, 1.0
	v_fmac_f32_e32 v34, v35, v34
	v_div_scale_f32 v35, vcc, v2, v30, v2
	v_mul_f32_e32 v36, v35, v34
	v_fma_f32 v37, -v33, v36, v35
	v_fmac_f32_e32 v36, v37, v34
	v_fma_f32 v33, -v33, v36, v35
	v_div_fmas_f32 v33, v33, v34, v36
	v_div_fixup_f32 v30, v33, v30, v2
	v_cvt_f32_f16_sdwa v33, v231 dst_sel:DWORD dst_unused:UNUSED_PAD src0_sel:WORD_1
	v_cvt_f32_f16_e32 v3, v231
	v_pk_mul_f32 v[26:27], v[26:27], v[30:31]
	v_mul_f32_e32 v31, 0xbfb8aa3b, v33
	v_mul_f32_e32 v30, 0xbfb8aa3b, v3
	v_exp_f32_e32 v30, v30
	v_exp_f32_e32 v31, v31
	v_cvt_pk_f16_f32 v2, v26, v27
	v_pk_add_f32 v[30:31], v[30:31], 1.0 op_sel_hi:[1,0]
	s_nop 0
	v_div_scale_f32 v34, s[4:5], v31, v31, v33
	v_rcp_f32_e32 v35, v34
	s_nop 0
	v_fma_f32 v36, -v34, v35, 1.0
	v_fmac_f32_e32 v35, v36, v35
	v_div_scale_f32 v36, vcc, v33, v31, v33
	v_mul_f32_e32 v37, v36, v35
	v_fma_f32 v38, -v34, v37, v36
	v_fmac_f32_e32 v37, v38, v35
	v_fma_f32 v34, -v34, v37, v36
	v_div_fmas_f32 v34, v34, v35, v37
	v_div_fixup_f32 v31, v34, v31, v33
	v_div_scale_f32 v33, s[4:5], v30, v30, v3
	v_rcp_f32_e32 v34, v33
	s_nop 0
	v_fma_f32 v35, -v33, v34, 1.0
	v_fmac_f32_e32 v34, v35, v34
	v_div_scale_f32 v35, vcc, v3, v30, v3
	v_mul_f32_e32 v36, v35, v34
	v_fma_f32 v37, -v33, v36, v35
	v_fmac_f32_e32 v36, v37, v34
	v_fma_f32 v33, -v33, v36, v35
	v_div_fmas_f32 v33, v33, v34, v36
	v_div_fixup_f32 v30, v33, v30, v3
	v_pk_mul_f32 v[28:29], v[28:29], v[30:31]
	v_cvt_pk_f16_f32 v3, v28, v29
	s_waitcnt vmcnt(5)
	v_cvt_f32_f16_sdwa v33, v232 dst_sel:DWORD dst_unused:UNUSED_PAD src0_sel:WORD_1
	v_cvt_f32_f16_e32 v30, v232
	s_waitcnt vmcnt(4)
	v_pk_add_f32 v[22:23], v[104:105], v[196:197]
	v_pk_add_f32 v[36:37], v[102:103], v[198:199]
	v_mul_f32_e32 v35, 0xbfb8aa3b, v33
	v_mul_f32_e32 v34, 0xbfb8aa3b, v30
	v_exp_f32_e32 v34, v34
	v_exp_f32_e32 v35, v35
	s_nop 0
	v_pk_add_f32 v[34:35], v[34:35], 1.0 op_sel_hi:[1,0]
	s_nop 0
	v_div_scale_f32 v38, s[4:5], v35, v35, v33
	v_rcp_f32_e32 v39, v38
	s_nop 0
	v_fma_f32 v40, -v38, v39, 1.0
	v_fmac_f32_e32 v39, v40, v39
	v_div_scale_f32 v40, vcc, v33, v35, v33
	v_mul_f32_e32 v41, v40, v39
	v_fma_f32 v42, -v38, v41, v40
	v_fmac_f32_e32 v41, v42, v39
	v_fma_f32 v38, -v38, v41, v40
	v_div_fmas_f32 v38, v38, v39, v41
	v_div_fixup_f32 v35, v38, v35, v33
	v_div_scale_f32 v33, s[4:5], v34, v34, v30
	v_rcp_f32_e32 v38, v33
	s_nop 0
	v_fma_f32 v39, -v33, v38, 1.0
	v_fmac_f32_e32 v38, v39, v38
	v_div_scale_f32 v39, vcc, v30, v34, v30
	v_mul_f32_e32 v40, v39, v38
	v_fma_f32 v41, -v33, v40, v39
	v_fmac_f32_e32 v40, v41, v38
	v_fma_f32 v33, -v33, v40, v39
	v_div_fmas_f32 v33, v33, v38, v40
	v_div_fixup_f32 v34, v33, v34, v30
	v_pk_mul_f32 v[22:23], v[22:23], v[34:35]
	v_cvt_f32_f16_sdwa v33, v233 dst_sel:DWORD dst_unused:UNUSED_PAD src0_sel:WORD_1
	v_cvt_f32_f16_e32 v35, v233
	v_cvt_pk_f16_f32 v34, v22, v23
	v_mul_f32_e32 v31, 0xbfb8aa3b, v33
	v_mul_f32_e32 v30, 0xbfb8aa3b, v35
	v_exp_f32_e32 v30, v30
	v_exp_f32_e32 v31, v31
	s_nop 0
	v_pk_add_f32 v[30:31], v[30:31], 1.0 op_sel_hi:[1,0]
	s_nop 0
	v_div_scale_f32 v38, s[4:5], v31, v31, v33
	v_rcp_f32_e32 v39, v38
	s_nop 0
	v_fma_f32 v40, -v38, v39, 1.0
	v_fmac_f32_e32 v39, v40, v39
	v_div_scale_f32 v40, vcc, v33, v31, v33
	v_mul_f32_e32 v41, v40, v39
	v_fma_f32 v42, -v38, v41, v40
	v_fmac_f32_e32 v41, v42, v39
	v_fma_f32 v38, -v38, v41, v40
	v_div_fmas_f32 v38, v38, v39, v41
	v_div_fixup_f32 v31, v38, v31, v33
	v_div_scale_f32 v33, s[4:5], v30, v30, v35
	v_rcp_f32_e32 v38, v33
	s_nop 0
	v_fma_f32 v39, -v33, v38, 1.0
	v_fmac_f32_e32 v38, v39, v38
	v_div_scale_f32 v39, vcc, v35, v30, v35
	v_mul_f32_e32 v40, v39, v38
	v_fma_f32 v41, -v33, v40, v39
	v_fmac_f32_e32 v40, v41, v38
	v_fma_f32 v33, -v33, v40, v39
	v_div_fmas_f32 v33, v33, v38, v40
	v_div_fixup_f32 v30, v33, v30, v35
	v_pk_mul_f32 v[30:31], v[36:37], v[30:31]
	v_add_u32_e32 v36, 0x4000, v32
	v_cvt_pk_f16_f32 v35, v30, v31
	ds_write2_b64 v36, v[2:3], v[34:35] offset0:64 offset1:68
	v_lshl_add_u64 v[2:3], v[88:89], 0, v[20:21]
	s_nop 0
	s_waitcnt vmcnt(3)
	v_cvt_f32_f16_sdwa v37, v234 dst_sel:DWORD dst_unused:UNUSED_PAD src0_sel:WORD_1
	v_cvt_f32_f16_e32 v2, v234
	s_waitcnt vmcnt(2)
	v_pk_add_f32 v[20:21], v[100:101], v[200:201]
	v_pk_add_f32 v[34:35], v[98:99], v[202:203]
	v_mul_f32_e32 v33, 0xbfb8aa3b, v37
	v_mul_f32_e32 v32, 0xbfb8aa3b, v2
	v_exp_f32_e32 v32, v32
	v_exp_f32_e32 v33, v33
	s_nop 0
	v_pk_add_f32 v[32:33], v[32:33], 1.0 op_sel_hi:[1,0]
	s_nop 0
	v_div_scale_f32 v38, s[4:5], v33, v33, v37
	v_rcp_f32_e32 v39, v38
	s_nop 0
	v_fma_f32 v40, -v38, v39, 1.0
	v_fmac_f32_e32 v39, v40, v39
	v_div_scale_f32 v40, vcc, v37, v33, v37
	v_mul_f32_e32 v41, v40, v39
	v_fma_f32 v42, -v38, v41, v40
	v_fmac_f32_e32 v41, v42, v39
	v_fma_f32 v38, -v38, v41, v40
	v_div_fmas_f32 v38, v38, v39, v41
	v_div_fixup_f32 v33, v38, v33, v37
	v_div_scale_f32 v37, s[4:5], v32, v32, v2
	v_rcp_f32_e32 v38, v37
	s_nop 0
	v_fma_f32 v39, -v37, v38, 1.0
	v_fmac_f32_e32 v38, v39, v38
	v_div_scale_f32 v39, vcc, v2, v32, v2
	v_mul_f32_e32 v40, v39, v38
	v_fma_f32 v41, -v37, v40, v39
	v_fmac_f32_e32 v40, v41, v38
	v_fma_f32 v37, -v37, v40, v39
	v_div_fmas_f32 v37, v37, v38, v40
	v_div_fixup_f32 v32, v37, v32, v2
	v_pk_mul_f32 v[32:33], v[20:21], v[32:33]
	v_cvt_f32_f16_sdwa v21, v235 dst_sel:DWORD dst_unused:UNUSED_PAD src0_sel:WORD_1
	v_cvt_f32_f16_e32 v37, v235
	v_cvt_pk_f16_f32 v20, v32, v33
	v_mul_f32_e32 v3, 0xbfb8aa3b, v21
	v_mul_f32_e32 v2, 0xbfb8aa3b, v37
	v_exp_f32_e32 v2, v2
	v_exp_f32_e32 v3, v3
	s_nop 0
	v_pk_add_f32 v[2:3], v[2:3], 1.0 op_sel_hi:[1,0]
	s_nop 0
	v_div_scale_f32 v38, s[4:5], v3, v3, v21
	v_rcp_f32_e32 v39, v38
	s_nop 0
	v_fma_f32 v40, -v38, v39, 1.0
	v_fmac_f32_e32 v39, v40, v39
	v_div_scale_f32 v40, vcc, v21, v3, v21
	v_mul_f32_e32 v41, v40, v39
	v_fma_f32 v42, -v38, v41, v40
	v_fmac_f32_e32 v41, v42, v39
	v_fma_f32 v38, -v38, v41, v40
	v_div_fmas_f32 v38, v38, v39, v41
	v_div_fixup_f32 v3, v38, v3, v21
	v_div_scale_f32 v21, s[4:5], v2, v2, v37
	v_rcp_f32_e32 v38, v21
	s_nop 0
	v_fma_f32 v39, -v21, v38, 1.0
	v_fmac_f32_e32 v38, v39, v38
	v_div_scale_f32 v39, vcc, v37, v2, v37
	v_mul_f32_e32 v40, v39, v38
	v_fma_f32 v41, -v21, v40, v39
	v_fmac_f32_e32 v40, v41, v38
	v_fma_f32 v21, -v21, v40, v39
	v_div_fmas_f32 v21, v21, v38, v40
	v_div_fixup_f32 v2, v21, v2, v37
	v_pk_mul_f32 v[34:35], v[34:35], v[2:3]
	v_lshl_add_u64 v[2:3], v[88:89], 0, v[24:25]
	s_nop 0
	v_cvt_pk_f16_f32 v21, v34, v35
	s_waitcnt vmcnt(1)
	v_cvt_f32_f16_sdwa v37, v236 dst_sel:DWORD dst_unused:UNUSED_PAD src0_sel:WORD_1
	v_cvt_f32_f16_e32 v24, v236
	s_waitcnt vmcnt(0)
	v_pk_add_f32 v[0:1], v[96:97], v[204:205]
	v_pk_add_f32 v[2:3], v[94:95], v[206:207]
	v_mul_f32_e32 v39, 0xbfb8aa3b, v37
	v_mul_f32_e32 v38, 0xbfb8aa3b, v24
	v_exp_f32_e32 v38, v38
	v_exp_f32_e32 v39, v39
	s_nop 0
	v_pk_add_f32 v[38:39], v[38:39], 1.0 op_sel_hi:[1,0]
	s_nop 0
	v_div_scale_f32 v40, s[4:5], v39, v39, v37
	v_rcp_f32_e32 v41, v40
	s_nop 0
	v_fma_f32 v42, -v40, v41, 1.0
	v_fmac_f32_e32 v41, v42, v41
	v_div_scale_f32 v42, vcc, v37, v39, v37
	v_mul_f32_e32 v43, v42, v41
	v_fma_f32 v44, -v40, v43, v42
	v_fmac_f32_e32 v43, v44, v41
	v_fma_f32 v40, -v40, v43, v42
	v_div_fmas_f32 v40, v40, v41, v43
	v_div_fixup_f32 v39, v40, v39, v37
	v_div_scale_f32 v37, s[4:5], v38, v38, v24
	v_rcp_f32_e32 v40, v37
	s_nop 0
	v_fma_f32 v41, -v37, v40, 1.0
	v_fmac_f32_e32 v40, v41, v40
	v_div_scale_f32 v41, vcc, v24, v38, v24
	v_mul_f32_e32 v42, v41, v40
	v_fma_f32 v43, -v37, v42, v41
	v_fmac_f32_e32 v42, v43, v40
	v_fma_f32 v37, -v37, v42, v41
	v_div_fmas_f32 v37, v37, v40, v42
	v_div_fixup_f32 v38, v37, v38, v24
	v_cvt_f32_f16_sdwa v37, v237 dst_sel:DWORD dst_unused:UNUSED_PAD src0_sel:WORD_1
	v_cvt_f32_f16_e32 v25, v237
	v_pk_mul_f32 v[0:1], v[0:1], v[38:39]
	v_mul_f32_e32 v39, 0xbfb8aa3b, v37
	v_mul_f32_e32 v38, 0xbfb8aa3b, v25
	v_exp_f32_e32 v38, v38
	v_exp_f32_e32 v39, v39
	v_cvt_pk_f16_f32 v24, v0, v1
	v_pk_add_f32 v[38:39], v[38:39], 1.0 op_sel_hi:[1,0]
	s_nop 0
	v_div_scale_f32 v40, s[4:5], v39, v39, v37
	v_rcp_f32_e32 v41, v40
	s_nop 0
	v_fma_f32 v42, -v40, v41, 1.0
	v_fmac_f32_e32 v41, v42, v41
	v_div_scale_f32 v42, vcc, v37, v39, v37
	v_mul_f32_e32 v43, v42, v41
	v_fma_f32 v44, -v40, v43, v42
	v_fmac_f32_e32 v43, v44, v41
	v_fma_f32 v40, -v40, v43, v42
	v_div_fmas_f32 v40, v40, v41, v43
	v_div_fixup_f32 v39, v40, v39, v37
	v_div_scale_f32 v37, s[4:5], v38, v38, v25
	v_rcp_f32_e32 v40, v37
	s_mov_b64 s[4:5], 0
	v_fma_f32 v41, -v37, v40, 1.0
	v_fmac_f32_e32 v40, v41, v40
	v_div_scale_f32 v41, vcc, v25, v38, v25
	v_mul_f32_e32 v42, v41, v40
	v_fma_f32 v43, -v37, v42, v41
	v_fmac_f32_e32 v42, v43, v40
	v_fma_f32 v37, -v37, v42, v41
	v_div_fmas_f32 v37, v37, v40, v42
	v_div_fixup_f32 v38, v37, v38, v25
	v_pk_mul_f32 v[2:3], v[2:3], v[38:39]
	v_mov_b32_e32 v39, v4
	v_mov_b32_e32 v4, v27
	v_mov_b32_e32 v38, v26
	v_pk_mul_f32 v[4:5], v[4:5], v[4:5]
	v_mov_b32_e32 v26, v28
	v_pk_fma_f32 v[4:5], v[38:39], v[38:39], v[4:5]
	v_mov_b32_e32 v27, v6
	v_mov_b32_e32 v6, v29
	v_pk_fma_f32 v[4:5], v[26:27], v[26:27], v[4:5]
	v_cvt_pk_f16_f32 v25, v2, v3
	v_pk_fma_f32 v[4:5], v[6:7], v[6:7], v[4:5]
	v_mov_b32_e32 v7, v8
	v_mov_b32_e32 v8, v23
	v_mov_b32_e32 v6, v22
	v_pk_mul_f32 v[8:9], v[8:9], v[8:9]
	v_pk_add_f32 v[4:5], v[92:93], v[4:5]
	v_pk_fma_f32 v[6:7], v[6:7], v[6:7], v[8:9]
	v_mov_b32_e32 v8, v30
	v_mov_b32_e32 v9, v10
	v_mov_b32_e32 v10, v31
	v_pk_fma_f32 v[6:7], v[8:9], v[8:9], v[6:7]
	s_and_b64 vcc, exec, s[40:41]
	v_pk_fma_f32 v[6:7], v[10:11], v[10:11], v[6:7]
	ds_write2_b64 v36, v[20:21], v[24:25] offset0:72 offset1:76
	v_pk_add_f32 v[4:5], v[4:5], v[6:7]
	v_mov_b32_e32 v7, v12
	v_mov_b32_e32 v12, v33
	v_mov_b32_e32 v6, v32
	v_pk_mul_f32 v[8:9], v[12:13], v[12:13]
	s_nop 0
	v_pk_fma_f32 v[6:7], v[6:7], v[6:7], v[8:9]
	v_mov_b32_e32 v8, v34
	v_mov_b32_e32 v9, v14
	v_mov_b32_e32 v14, v35
	v_pk_fma_f32 v[6:7], v[8:9], v[8:9], v[6:7]
	s_nop 0
	v_pk_fma_f32 v[6:7], v[14:15], v[14:15], v[6:7]
	s_nop 0
	v_pk_add_f32 v[4:5], v[4:5], v[6:7]
	v_mov_b32_e32 v7, v16
	v_mov_b32_e32 v16, v1
	v_mov_b32_e32 v6, v0
	v_pk_mul_f32 v[0:1], v[16:17], v[16:17]
	s_nop 0
	v_pk_fma_f32 v[0:1], v[6:7], v[6:7], v[0:1]
	v_mov_b32_e32 v6, v2
	v_mov_b32_e32 v7, v18
	v_mov_b32_e32 v18, v3
	v_pk_fma_f32 v[0:1], v[6:7], v[6:7], v[0:1]
	s_nop 0
	v_pk_fma_f32 v[0:1], v[18:19], v[18:19], v[0:1]
	s_nop 0
	v_pk_add_f32 v[92:93], v[4:5], v[0:1]
	s_cbranch_vccnz .LBB0_93

.LBB0_104:
	v_or_b32_e32 v86, s6, v103
	v_ashrrev_i32_e32 v87, 31, v86
	v_lshlrev_b64 v[86:87], 14, v[86:87]
	v_lshl_add_u64 v[130:131], v[46:47], 0, v[86:87]
	v_lshl_add_u64 v[142:143], v[130:131], 0, v[168:169]
	v_cndmask_b32_e64 v49, 0, 1, s[4:5]
	v_cmp_ne_u32_e32 vcc, 1, v49
	s_mov_b64 s[4:5], 0
	s_and_b64 vcc, exec, vcc
	v_lshl_add_u64 v[144:145], v[142:143], 0, s[34:35]
	v_lshl_add_u64 v[146:147], v[142:143], 0, s[26:27]
	v_lshl_add_u64 v[148:149], v[142:143], 0, s[86:87]
	global_load_dwordx4 v[176:179], v[142:143], off
	global_load_dwordx4 v[180:183], v[144:145], off
	global_load_dwordx4 v[184:187], v[146:147], off
	global_load_dwordx4 v[188:191], v[148:149], off
	global_load_dwordx4 v[192:195], v[142:143], off offset:64
	global_load_dwordx4 v[196:199], v[144:145], off offset:64
	global_load_dwordx4 v[200:203], v[146:147], off offset:64
	global_load_dwordx4 v[204:207], v[148:149], off offset:64
	global_load_dwordx4 v[222:225], v[142:143], off offset:128
	global_load_dwordx4 v[226:229], v[144:145], off offset:128
	global_load_dwordx4 v[230:233], v[146:147], off offset:128
	global_load_dwordx4 v[234:237], v[148:149], off offset:128
	global_load_dwordx4 v[238:241], v[142:143], off offset:192
	global_load_dwordx4 v[242:245], v[144:145], off offset:192
	global_load_dwordx4 v[246:249], v[146:147], off offset:192
	global_load_dwordx4 v[152:155], v[148:149], off offset:192
	s_waitcnt lgkmcnt(0)
	s_waitcnt vmcnt(15)
	v_mfma_f32_16x16x32_f16 v[106:109], v[176:179], v[0:3], 0
	v_mfma_f32_16x16x32_f16 v[110:113], v[176:179], v[8:11], 0
	s_waitcnt vmcnt(14)
	v_mfma_f32_16x16x32_f16 v[114:117], v[180:183], v[0:3], 0
	v_mfma_f32_16x16x32_f16 v[118:121], v[180:183], v[8:11], 0
	s_waitcnt vmcnt(13)
	v_mfma_f32_16x16x32_f16 v[126:129], v[184:187], v[0:3], 0
	v_mfma_f32_16x16x32_f16 v[88:91], v[184:187], v[8:11], 0
	s_waitcnt vmcnt(12)
	v_mfma_f32_16x16x32_f16 v[134:137], v[188:191], v[0:3], 0
	v_mfma_f32_16x16x32_f16 v[122:125], v[188:191], v[8:11], 0
	s_waitcnt vmcnt(11)
	v_mfma_f32_16x16x32_f16 v[106:109], v[192:195], v[4:7], v[106:109]
	v_mfma_f32_16x16x32_f16 v[110:113], v[192:195], v[12:15], v[110:113]
	s_waitcnt vmcnt(10)
	v_mfma_f32_16x16x32_f16 v[114:117], v[196:199], v[4:7], v[114:117]
	v_mfma_f32_16x16x32_f16 v[118:121], v[196:199], v[12:15], v[118:121]
	s_waitcnt vmcnt(9)
	v_mfma_f32_16x16x32_f16 v[126:129], v[200:203], v[4:7], v[126:129]
	v_mfma_f32_16x16x32_f16 v[88:91], v[200:203], v[12:15], v[88:91]
	s_waitcnt vmcnt(8)
	v_mfma_f32_16x16x32_f16 v[134:137], v[204:207], v[4:7], v[134:137]
	v_mfma_f32_16x16x32_f16 v[122:125], v[204:207], v[12:15], v[122:125]
	s_waitcnt vmcnt(7)
	v_mfma_f32_16x16x32_f16 v[106:109], v[222:225], v[16:19], v[106:109]
	v_mfma_f32_16x16x32_f16 v[110:113], v[222:225], v[24:27], v[110:113]
	s_waitcnt vmcnt(6)
	v_mfma_f32_16x16x32_f16 v[114:117], v[226:229], v[16:19], v[114:117]
	v_mfma_f32_16x16x32_f16 v[118:121], v[226:229], v[24:27], v[118:121]
	s_waitcnt vmcnt(5)
	v_mfma_f32_16x16x32_f16 v[126:129], v[230:233], v[16:19], v[126:129]
	v_mfma_f32_16x16x32_f16 v[88:91], v[230:233], v[24:27], v[88:91]
	s_waitcnt vmcnt(4)
	v_mfma_f32_16x16x32_f16 v[134:137], v[234:237], v[16:19], v[134:137]
	v_mfma_f32_16x16x32_f16 v[122:125], v[234:237], v[24:27], v[122:125]
	s_waitcnt vmcnt(3)
	v_mfma_f32_16x16x32_f16 v[106:109], v[238:241], v[20:23], v[106:109]
	v_mfma_f32_16x16x32_f16 v[110:113], v[238:241], v[28:31], v[110:113]
	s_waitcnt vmcnt(2)
	v_mfma_f32_16x16x32_f16 v[114:117], v[242:245], v[20:23], v[114:117]
	v_mfma_f32_16x16x32_f16 v[118:121], v[242:245], v[28:31], v[118:121]
	s_waitcnt vmcnt(1)
	v_mfma_f32_16x16x32_f16 v[126:129], v[246:249], v[20:23], v[126:129]
	v_mfma_f32_16x16x32_f16 v[88:91], v[246:249], v[28:31], v[88:91]
	s_waitcnt vmcnt(0)
	v_mfma_f32_16x16x32_f16 v[134:137], v[152:155], v[20:23], v[134:137]
	v_mfma_f32_16x16x32_f16 v[122:125], v[152:155], v[28:31], v[122:125]
	s_nop 7
	v_lshl_add_u32 v49, s6, 7, v104
	v_add_u32_e32 v49, 0xc400, v49
	s_mov_b32 s6, 1
	ds_read2_b32 v[86:87], v49 offset1:16
	s_waitcnt lgkmcnt(0)
	v_pk_fma_f32 v[84:85], v[106:107], v[86:87], v[84:85] op_sel_hi:[1,0,1]
	v_mov_b32_e32 v106, v87
	v_pk_fma_f32 v[68:69], v[110:111], v[106:107], v[68:69] op_sel_hi:[1,0,1]
	v_pk_fma_f32 v[82:83], v[108:109], v[86:87], v[82:83] op_sel_hi:[1,0,1]
	v_pk_fma_f32 v[66:67], v[112:113], v[106:107], v[66:67] op_sel_hi:[1,0,1]
	v_pk_fma_f32 v[80:81], v[114:115], v[86:87], v[80:81] op_sel_hi:[1,0,1]
	v_pk_fma_f32 v[64:65], v[118:119], v[106:107], v[64:65] op_sel_hi:[1,0,1]
	v_pk_fma_f32 v[78:79], v[116:117], v[86:87], v[78:79] op_sel_hi:[1,0,1]
	v_pk_fma_f32 v[62:63], v[120:121], v[106:107], v[62:63] op_sel_hi:[1,0,1]
	v_pk_fma_f32 v[76:77], v[126:127], v[86:87], v[76:77] op_sel_hi:[1,0,1]
	v_pk_fma_f32 v[60:61], v[88:89], v[106:107], v[60:61] op_sel_hi:[1,0,1]
	v_pk_fma_f32 v[74:75], v[128:129], v[86:87], v[74:75] op_sel_hi:[1,0,1]
	v_pk_fma_f32 v[58:59], v[90:91], v[106:107], v[58:59] op_sel_hi:[1,0,1]
	v_pk_fma_f32 v[72:73], v[134:135], v[86:87], v[72:73] op_sel_hi:[1,0,1]
	v_fma_f32 v70, v136, v86, v70
	v_fma_f32 v71, v137, v86, v71
	v_pk_fma_f32 v[56:57], v[122:123], v[106:107], v[56:57] op_sel_hi:[1,0,1]
	v_pk_fma_f32 v[54:55], v[124:125], v[106:107], v[54:55] op_sel_hi:[1,0,1]
	s_cbranch_vccz .LBB0_104
	v_lshl_or_b32 v2, v102, 6, v99
	v_ashrrev_i32_e32 v3, 31, v2
	v_lshlrev_b64 v[26:27], 1, v[2:3]
	v_lshlrev_b64 v[28:29], 2, v[2:3]
	v_lshl_add_u64 v[238:239], v[42:43], 0, v[26:27]
	v_lshl_add_u64 v[240:241], v[44:45], 0, v[26:27]
	v_lshl_add_u64 v[242:243], v[40:41], 0, v[28:29]
	v_lshl_add_u64 v[244:245], v[38:39], 0, v[28:29]
	global_load_dwordx2 v[222:223], v[238:239], off
	global_load_dwordx4 v[176:179], v[242:243], off
	global_load_dwordx2 v[224:225], v[238:239], off offset:32
	global_load_dwordx4 v[180:183], v[242:243], off offset:64
	global_load_dwordx2 v[226:227], v[238:239], off offset:64
	global_load_dwordx4 v[184:187], v[242:243], off offset:128
	global_load_dwordx2 v[228:229], v[238:239], off offset:96
	global_load_dwordx4 v[188:191], v[242:243], off offset:192
	global_load_dwordx2 v[230:231], v[240:241], off
	global_load_dwordx4 v[192:195], v[244:245], off
	global_load_dwordx2 v[232:233], v[240:241], off offset:32
	global_load_dwordx4 v[196:199], v[244:245], off offset:64
	global_load_dwordx2 v[234:235], v[240:241], off offset:64
	global_load_dwordx4 v[200:203], v[244:245], off offset:128
	global_load_dwordx2 v[236:237], v[240:241], off offset:96
	global_load_dwordx4 v[204:207], v[244:245], off offset:192
	v_lshl_add_u64 v[4:5], v[42:43], 0, v[26:27]
	v_lshl_add_u64 v[0:1], v[40:41], 0, v[28:29]
	s_nop 0
	v_lshlrev_b32_e32 v49, 1, v2
	s_waitcnt vmcnt(15)
	v_cvt_f32_f16_sdwa v3, v222 dst_sel:DWORD dst_unused:UNUSED_PAD src0_sel:WORD_1
	v_cvt_f32_f16_e32 v8, v222
	s_waitcnt vmcnt(14)
	v_pk_add_f32 v[4:5], v[84:85], v[176:177]
	v_pk_add_f32 v[6:7], v[82:83], v[178:179]
	v_mul_f32_e32 v11, 0xbfb8aa3b, v3
	v_mul_f32_e32 v10, 0xbfb8aa3b, v8
	v_exp_f32_e32 v10, v10
	v_exp_f32_e32 v11, v11
	s_nop 0
	v_pk_add_f32 v[10:11], v[10:11], 1.0 op_sel_hi:[1,0]
	s_nop 0
	v_div_scale_f32 v12, s[4:5], v11, v11, v3
	v_rcp_f32_e32 v13, v12
	s_nop 0
	v_fma_f32 v14, -v12, v13, 1.0
	v_fmac_f32_e32 v13, v14, v13
	v_div_scale_f32 v14, vcc, v3, v11, v3
	v_mul_f32_e32 v15, v14, v13
	v_fma_f32 v16, -v12, v15, v14
	v_fmac_f32_e32 v15, v16, v13
	v_fma_f32 v12, -v12, v15, v14
	v_div_fmas_f32 v12, v12, v13, v15
	v_div_fixup_f32 v11, v12, v11, v3
	v_div_scale_f32 v3, s[4:5], v10, v10, v8
	v_rcp_f32_e32 v12, v3
	s_nop 0
	v_fma_f32 v13, -v3, v12, 1.0
	v_fmac_f32_e32 v12, v13, v12
	v_div_scale_f32 v13, vcc, v8, v10, v8
	v_mul_f32_e32 v14, v13, v12
	v_fma_f32 v15, -v3, v14, v13
	v_fmac_f32_e32 v14, v15, v12
	v_fma_f32 v3, -v3, v14, v13
	v_div_fmas_f32 v3, v3, v12, v14
	v_div_fixup_f32 v10, v3, v10, v8
	v_pk_mul_f32 v[4:5], v[4:5], v[10:11]
	v_cvt_f32_f16_sdwa v3, v223 dst_sel:DWORD dst_unused:UNUSED_PAD src0_sel:WORD_1
	v_cvt_f32_f16_e32 v10, v223
	v_cvt_pk_f16_f32 v12, v4, v5
	v_mul_f32_e32 v9, 0xbfb8aa3b, v3
	v_mul_f32_e32 v8, 0xbfb8aa3b, v10
	v_exp_f32_e32 v8, v8
	v_exp_f32_e32 v9, v9
	s_nop 0
	v_pk_add_f32 v[8:9], v[8:9], 1.0 op_sel_hi:[1,0]
	s_nop 0
	v_div_scale_f32 v11, s[4:5], v9, v9, v3
	v_rcp_f32_e32 v13, v11
	s_nop 0
	v_fma_f32 v14, -v11, v13, 1.0
	v_fmac_f32_e32 v13, v14, v13
	v_div_scale_f32 v14, vcc, v3, v9, v3
	v_mul_f32_e32 v15, v14, v13
	v_fma_f32 v16, -v11, v15, v14
	v_fmac_f32_e32 v15, v16, v13
	v_fma_f32 v11, -v11, v15, v14
	v_div_fmas_f32 v11, v11, v13, v15
	v_div_fixup_f32 v9, v11, v9, v3
	v_div_scale_f32 v3, s[4:5], v8, v8, v10
	v_rcp_f32_e32 v11, v3
	s_nop 0
	v_fma_f32 v13, -v3, v11, 1.0
	v_fmac_f32_e32 v11, v13, v11
	v_div_scale_f32 v13, vcc, v10, v8, v10
	v_mul_f32_e32 v14, v13, v11
	v_fma_f32 v15, -v3, v14, v13
	v_fmac_f32_e32 v14, v15, v11
	v_fma_f32 v3, -v3, v14, v13
	v_div_fmas_f32 v3, v3, v11, v14
	v_div_fixup_f32 v8, v3, v8, v10
	v_pk_mul_f32 v[6:7], v[6:7], v[8:9]
	v_or_b32_e32 v8, 16, v2
	v_ashrrev_i32_e32 v9, 31, v8
	v_lshlrev_b64 v[22:23], 1, v[8:9]
	v_lshl_add_u64 v[8:9], v[42:43], 0, v[22:23]
	s_nop 0
	v_add_u32_e32 v3, v93, v49
	v_cvt_pk_f16_f32 v13, v6, v7
	v_add_u32_e32 v51, 0x4000, v3
	v_lshl_add_u64 v[22:23], v[44:45], 0, v[22:23]
	v_add_u32_e32 v49, v92, v49
	v_add_u32_e32 v49, 0x4000, v49
	s_waitcnt vmcnt(13)
	v_cvt_f32_f16_sdwa v18, v224 dst_sel:DWORD dst_unused:UNUSED_PAD src0_sel:WORD_1
	v_cvt_f32_f16_e32 v14, v224
	s_waitcnt vmcnt(12)
	v_pk_add_f32 v[8:9], v[80:81], v[180:181]
	v_pk_add_f32 v[10:11], v[78:79], v[182:183]
	v_mul_f32_e32 v17, 0xbfb8aa3b, v18
	v_mul_f32_e32 v16, 0xbfb8aa3b, v14
	v_exp_f32_e32 v16, v16
	v_exp_f32_e32 v17, v17
	s_nop 0
	v_pk_add_f32 v[16:17], v[16:17], 1.0 op_sel_hi:[1,0]
	s_nop 0
	v_div_scale_f32 v19, s[4:5], v17, v17, v18
	v_rcp_f32_e32 v20, v19
	s_nop 0
	v_fma_f32 v21, -v19, v20, 1.0
	v_fmac_f32_e32 v20, v21, v20
	v_div_scale_f32 v21, vcc, v18, v17, v18
	v_mul_f32_e32 v24, v21, v20
	v_fma_f32 v25, -v19, v24, v21
	v_fmac_f32_e32 v24, v25, v20
	v_fma_f32 v19, -v19, v24, v21
	v_div_fmas_f32 v19, v19, v20, v24
	v_div_fixup_f32 v17, v19, v17, v18
	v_div_scale_f32 v18, s[4:5], v16, v16, v14
	v_rcp_f32_e32 v19, v18
	s_nop 0
	v_fma_f32 v20, -v18, v19, 1.0
	v_fmac_f32_e32 v19, v20, v19
	v_div_scale_f32 v20, vcc, v14, v16, v14
	v_mul_f32_e32 v21, v20, v19
	v_fma_f32 v24, -v18, v21, v20
	v_fmac_f32_e32 v21, v24, v19
	v_fma_f32 v18, -v18, v21, v20
	v_div_fmas_f32 v18, v18, v19, v21
	v_div_fixup_f32 v16, v18, v16, v14
	v_cvt_f32_f16_sdwa v18, v225 dst_sel:DWORD dst_unused:UNUSED_PAD src0_sel:WORD_1
	v_cvt_f32_f16_e32 v15, v225
	v_pk_mul_f32 v[8:9], v[8:9], v[16:17]
	v_mul_f32_e32 v17, 0xbfb8aa3b, v18
	v_mul_f32_e32 v16, 0xbfb8aa3b, v15
	v_exp_f32_e32 v16, v16
	v_exp_f32_e32 v17, v17
	v_cvt_pk_f16_f32 v14, v8, v9
	v_pk_add_f32 v[16:17], v[16:17], 1.0 op_sel_hi:[1,0]
	s_nop 0
	v_div_scale_f32 v19, s[4:5], v17, v17, v18
	v_rcp_f32_e32 v20, v19
	s_nop 0
	v_fma_f32 v21, -v19, v20, 1.0
	v_fmac_f32_e32 v20, v21, v20
	v_div_scale_f32 v21, vcc, v18, v17, v18
	v_mul_f32_e32 v24, v21, v20
	v_fma_f32 v25, -v19, v24, v21
	v_fmac_f32_e32 v24, v25, v20
	v_fma_f32 v19, -v19, v24, v21
	v_div_fmas_f32 v19, v19, v20, v24
	v_div_fixup_f32 v17, v19, v17, v18
	v_div_scale_f32 v18, s[4:5], v16, v16, v15
	v_rcp_f32_e32 v19, v18
	s_nop 0
	v_fma_f32 v20, -v18, v19, 1.0
	v_fmac_f32_e32 v19, v20, v19
	v_div_scale_f32 v20, vcc, v15, v16, v15
	v_mul_f32_e32 v21, v20, v19
	v_fma_f32 v24, -v18, v21, v20
	v_fmac_f32_e32 v21, v24, v19
	v_fma_f32 v18, -v18, v21, v20
	v_div_fmas_f32 v18, v18, v19, v21
	v_div_fixup_f32 v16, v18, v16, v15
	v_pk_mul_f32 v[10:11], v[10:11], v[16:17]
	s_nop 0
	v_cvt_pk_f16_f32 v15, v10, v11
	ds_write2_b64 v51, v[12:13], v[14:15] offset0:64 offset1:68
	v_or_b32_e32 v12, 32, v2
	v_ashrrev_i32_e32 v13, 31, v12
	v_lshlrev_b64 v[20:21], 1, v[12:13]
	v_lshl_add_u64 v[12:13], v[42:43], 0, v[20:21]
	s_nop 0
	v_or_b32_e32 v2, 48, v2
	s_waitcnt vmcnt(11)
	v_cvt_f32_f16_sdwa v3, v226 dst_sel:DWORD dst_unused:UNUSED_PAD src0_sel:WORD_1
	v_cvt_f32_f16_e32 v16, v226
	s_waitcnt vmcnt(10)
	v_pk_add_f32 v[12:13], v[76:77], v[184:185]
	v_pk_add_f32 v[14:15], v[74:75], v[186:187]
	v_mul_f32_e32 v19, 0xbfb8aa3b, v3
	v_mul_f32_e32 v18, 0xbfb8aa3b, v16
	v_exp_f32_e32 v18, v18
	v_exp_f32_e32 v19, v19
	s_nop 0
	v_pk_add_f32 v[18:19], v[18:19], 1.0 op_sel_hi:[1,0]
	s_nop 0
	v_div_scale_f32 v24, s[4:5], v19, v19, v3
	v_rcp_f32_e32 v25, v24
	s_nop 0
	v_fma_f32 v30, -v24, v25, 1.0
	v_fmac_f32_e32 v25, v30, v25
	v_div_scale_f32 v30, vcc, v3, v19, v3
	v_mul_f32_e32 v31, v30, v25
	v_fma_f32 v53, -v24, v31, v30
	v_fmac_f32_e32 v31, v53, v25
	v_fma_f32 v24, -v24, v31, v30
	v_div_fmas_f32 v24, v24, v25, v31
	v_div_fixup_f32 v19, v24, v19, v3
	v_div_scale_f32 v3, s[4:5], v18, v18, v16
	v_rcp_f32_e32 v24, v3
	s_nop 0
	v_fma_f32 v25, -v3, v24, 1.0
	v_fmac_f32_e32 v24, v25, v24
	v_div_scale_f32 v25, vcc, v16, v18, v16
	v_mul_f32_e32 v30, v25, v24
	v_fma_f32 v31, -v3, v30, v25
	v_fmac_f32_e32 v30, v31, v24
	v_fma_f32 v3, -v3, v30, v25
	v_div_fmas_f32 v3, v3, v24, v30
	v_div_fixup_f32 v18, v3, v18, v16
	v_pk_mul_f32 v[12:13], v[12:13], v[18:19]
	v_cvt_f32_f16_sdwa v3, v227 dst_sel:DWORD dst_unused:UNUSED_PAD src0_sel:WORD_1
	v_cvt_f32_f16_e32 v18, v227
	v_cvt_pk_f16_f32 v30, v12, v13
	v_mul_f32_e32 v17, 0xbfb8aa3b, v3
	v_mul_f32_e32 v16, 0xbfb8aa3b, v18
	v_exp_f32_e32 v16, v16
	v_exp_f32_e32 v17, v17
	s_nop 0
	v_pk_add_f32 v[16:17], v[16:17], 1.0 op_sel_hi:[1,0]
	s_nop 0
	v_div_scale_f32 v19, s[4:5], v17, v17, v3
	v_rcp_f32_e32 v24, v19
	s_nop 0
	v_fma_f32 v25, -v19, v24, 1.0
	v_fmac_f32_e32 v24, v25, v24
	v_div_scale_f32 v25, vcc, v3, v17, v3
	v_mul_f32_e32 v31, v25, v24
	v_fma_f32 v53, -v19, v31, v25
	v_fmac_f32_e32 v31, v53, v24
	v_fma_f32 v19, -v19, v31, v25
	v_div_fmas_f32 v19, v19, v24, v31
	v_div_fixup_f32 v17, v19, v17, v3
	v_div_scale_f32 v3, s[4:5], v16, v16, v18
	v_rcp_f32_e32 v19, v3
	s_nop 0
	v_fma_f32 v24, -v3, v19, 1.0
	v_fmac_f32_e32 v19, v24, v19
	v_div_scale_f32 v24, vcc, v18, v16, v18
	v_mul_f32_e32 v25, v24, v19
	v_fma_f32 v31, -v3, v25, v24
	v_fmac_f32_e32 v25, v31, v19
	v_fma_f32 v3, -v3, v25, v24
	v_div_fmas_f32 v3, v3, v19, v25
	v_div_fixup_f32 v16, v3, v16, v18
	v_ashrrev_i32_e32 v3, 31, v2
	v_lshlrev_b64 v[24:25], 1, v[2:3]
	v_lshl_add_u64 v[2:3], v[42:43], 0, v[24:25]
	s_nop 0
	v_pk_mul_f32 v[14:15], v[14:15], v[16:17]
	s_waitcnt vmcnt(9)
	v_cvt_f32_f16_sdwa v53, v228 dst_sel:DWORD dst_unused:UNUSED_PAD src0_sel:WORD_1
	v_cvt_f32_f16_e32 v18, v228
	s_waitcnt vmcnt(8)
	v_pk_add_f32 v[0:1], v[72:73], v[188:189]
	v_pk_add_f32 v[2:3], v[70:71], v[190:191]
	v_mul_f32_e32 v17, 0xbfb8aa3b, v53
	v_mul_f32_e32 v16, 0xbfb8aa3b, v18
	v_exp_f32_e32 v16, v16
	v_exp_f32_e32 v17, v17
	v_cvt_pk_f16_f32 v31, v14, v15
	v_pk_add_f32 v[16:17], v[16:17], 1.0 op_sel_hi:[1,0]
	s_nop 0
	v_div_scale_f32 v72, s[4:5], v17, v17, v53
	v_rcp_f32_e32 v73, v72
	s_nop 0
	v_fma_f32 v74, -v72, v73, 1.0
	v_fmac_f32_e32 v73, v74, v73
	v_div_scale_f32 v74, vcc, v53, v17, v53
	v_mul_f32_e32 v75, v74, v73
	v_fma_f32 v76, -v72, v75, v74
	v_fmac_f32_e32 v75, v76, v73
	v_fma_f32 v72, -v72, v75, v74
	v_div_fmas_f32 v72, v72, v73, v75
	v_div_fixup_f32 v17, v72, v17, v53
	v_div_scale_f32 v53, s[4:5], v16, v16, v18
	v_rcp_f32_e32 v72, v53
	s_nop 0
	v_fma_f32 v73, -v53, v72, 1.0
	v_fmac_f32_e32 v72, v73, v72
	v_div_scale_f32 v73, vcc, v18, v16, v18
	v_mul_f32_e32 v74, v73, v72
	v_fma_f32 v75, -v53, v74, v73
	v_fmac_f32_e32 v74, v75, v72
	v_fma_f32 v53, -v53, v74, v73
	v_div_fmas_f32 v53, v53, v72, v74
	v_div_fixup_f32 v16, v53, v16, v18
	v_pk_mul_f32 v[16:17], v[0:1], v[16:17]
	v_cvt_f32_f16_sdwa v1, v229 dst_sel:DWORD dst_unused:UNUSED_PAD src0_sel:WORD_1
	v_cvt_f32_f16_e32 v53, v229
	v_cvt_pk_f16_f32 v0, v16, v17
	v_mul_f32_e32 v19, 0xbfb8aa3b, v1
	v_mul_f32_e32 v18, 0xbfb8aa3b, v53
	v_exp_f32_e32 v18, v18
	v_exp_f32_e32 v19, v19
	s_nop 0
	v_pk_add_f32 v[18:19], v[18:19], 1.0 op_sel_hi:[1,0]
	s_nop 0
	v_div_scale_f32 v70, s[4:5], v19, v19, v1
	v_rcp_f32_e32 v71, v70
	s_nop 0
	v_fma_f32 v72, -v70, v71, 1.0
	v_fmac_f32_e32 v71, v72, v71
	v_div_scale_f32 v72, vcc, v1, v19, v1
	v_mul_f32_e32 v73, v72, v71
	v_fma_f32 v74, -v70, v73, v72
	v_fmac_f32_e32 v73, v74, v71
	v_fma_f32 v70, -v70, v73, v72
	v_div_fmas_f32 v70, v70, v71, v73
	v_div_fixup_f32 v19, v70, v19, v1
	v_div_scale_f32 v1, s[4:5], v18, v18, v53
	v_rcp_f32_e32 v70, v1
	s_nop 0
	v_fma_f32 v71, -v1, v70, 1.0
	v_fmac_f32_e32 v70, v71, v70
	v_div_scale_f32 v71, vcc, v53, v18, v53
	v_mul_f32_e32 v72, v71, v70
	v_fma_f32 v73, -v1, v72, v71
	v_fmac_f32_e32 v72, v73, v70
	v_fma_f32 v1, -v1, v72, v71
	v_div_fmas_f32 v1, v1, v70, v72
	v_div_fixup_f32 v18, v1, v18, v53
	v_pk_mul_f32 v[18:19], v[2:3], v[18:19]
	v_lshl_add_u64 v[2:3], v[44:45], 0, v[26:27]
	v_cvt_pk_f16_f32 v1, v18, v19
	ds_write2_b64 v51, v[30:31], v[0:1] offset0:72 offset1:76
	v_lshl_add_u64 v[0:1], v[38:39], 0, v[28:29]
	s_nop 0
	s_waitcnt vmcnt(7)
	v_cvt_f32_f16_sdwa v51, v230 dst_sel:DWORD dst_unused:UNUSED_PAD src0_sel:WORD_1
	v_cvt_f32_f16_e32 v2, v230
	s_waitcnt vmcnt(6)
	v_pk_add_f32 v[26:27], v[68:69], v[192:193]
	v_pk_add_f32 v[28:29], v[66:67], v[194:195]
	v_mul_f32_e32 v31, 0xbfb8aa3b, v51
	v_mul_f32_e32 v30, 0xbfb8aa3b, v2
	v_exp_f32_e32 v30, v30
	v_exp_f32_e32 v31, v31
	s_nop 0
	v_pk_add_f32 v[30:31], v[30:31], 1.0 op_sel_hi:[1,0]
	s_nop 0
	v_div_scale_f32 v53, s[4:5], v31, v31, v51
	v_rcp_f32_e32 v68, v53
	s_nop 0
	v_fma_f32 v69, -v53, v68, 1.0
	v_fmac_f32_e32 v68, v69, v68
	v_div_scale_f32 v69, vcc, v51, v31, v51
	v_mul_f32_e32 v70, v69, v68
	v_fma_f32 v71, -v53, v70, v69
	v_fmac_f32_e32 v70, v71, v68
	v_fma_f32 v53, -v53, v70, v69
	v_div_fmas_f32 v53, v53, v68, v70
	v_div_fixup_f32 v31, v53, v31, v51
	v_div_scale_f32 v51, s[4:5], v30, v30, v2
	v_rcp_f32_e32 v53, v51
	s_nop 0
	v_fma_f32 v68, -v51, v53, 1.0
	v_fmac_f32_e32 v53, v68, v53
	v_div_scale_f32 v68, vcc, v2, v30, v2
	v_mul_f32_e32 v69, v68, v53
	v_fma_f32 v70, -v51, v69, v68
	v_fmac_f32_e32 v69, v70, v53
	v_fma_f32 v51, -v51, v69, v68
	v_div_fmas_f32 v51, v51, v53, v69
	v_div_fixup_f32 v30, v51, v30, v2
	v_cvt_f32_f16_sdwa v51, v231 dst_sel:DWORD dst_unused:UNUSED_PAD src0_sel:WORD_1
	v_cvt_f32_f16_e32 v3, v231
	v_pk_mul_f32 v[26:27], v[26:27], v[30:31]
	v_mul_f32_e32 v31, 0xbfb8aa3b, v51
	v_mul_f32_e32 v30, 0xbfb8aa3b, v3
	v_exp_f32_e32 v30, v30
	v_exp_f32_e32 v31, v31
	v_cvt_pk_f16_f32 v2, v26, v27
	v_pk_add_f32 v[30:31], v[30:31], 1.0 op_sel_hi:[1,0]
	s_nop 0
	v_div_scale_f32 v53, s[4:5], v31, v31, v51
	v_rcp_f32_e32 v66, v53
	s_nop 0
	v_fma_f32 v67, -v53, v66, 1.0
	v_fmac_f32_e32 v66, v67, v66
	v_div_scale_f32 v67, vcc, v51, v31, v51
	v_mul_f32_e32 v68, v67, v66
	v_fma_f32 v69, -v53, v68, v67
	v_fmac_f32_e32 v68, v69, v66
	v_fma_f32 v53, -v53, v68, v67
	v_div_fmas_f32 v53, v53, v66, v68
	v_div_fixup_f32 v31, v53, v31, v51
	v_div_scale_f32 v51, s[4:5], v30, v30, v3
	v_rcp_f32_e32 v53, v51
	s_nop 0
	v_fma_f32 v66, -v51, v53, 1.0
	v_fmac_f32_e32 v53, v66, v53
	v_div_scale_f32 v66, vcc, v3, v30, v3
	v_mul_f32_e32 v67, v66, v53
	v_fma_f32 v68, -v51, v67, v66
	v_fmac_f32_e32 v67, v68, v53
	v_fma_f32 v51, -v51, v67, v66
	v_div_fmas_f32 v51, v51, v53, v67
	v_div_fixup_f32 v30, v51, v30, v3
	v_pk_mul_f32 v[28:29], v[28:29], v[30:31]
	v_cvt_pk_f16_f32 v3, v28, v29
	s_waitcnt vmcnt(5)
	v_cvt_f32_f16_sdwa v51, v232 dst_sel:DWORD dst_unused:UNUSED_PAD src0_sel:WORD_1
	v_cvt_f32_f16_e32 v30, v232
	s_waitcnt vmcnt(4)
	v_pk_add_f32 v[22:23], v[64:65], v[196:197]
	v_pk_add_f32 v[62:63], v[62:63], v[198:199]
	v_mul_f32_e32 v53, 0xbfb8aa3b, v30
	v_exp_f32_e32 v64, v53
	v_mul_f32_e32 v53, 0xbfb8aa3b, v51
	v_exp_f32_e32 v65, v53
	s_nop 0
	v_pk_add_f32 v[64:65], v[64:65], 1.0 op_sel_hi:[1,0]
	s_nop 0
	v_div_scale_f32 v53, s[4:5], v65, v65, v51
	v_rcp_f32_e32 v66, v53
	s_nop 0
	v_fma_f32 v67, -v53, v66, 1.0
	v_fmac_f32_e32 v66, v67, v66
	v_div_scale_f32 v67, vcc, v51, v65, v51
	v_mul_f32_e32 v70, v67, v66
	v_fma_f32 v71, -v53, v70, v67
	v_fmac_f32_e32 v70, v71, v66
	v_fma_f32 v53, -v53, v70, v67
	v_div_fmas_f32 v53, v53, v66, v70
	v_div_fixup_f32 v65, v53, v65, v51
	v_div_scale_f32 v51, s[4:5], v64, v64, v30
	v_rcp_f32_e32 v53, v51
	s_nop 0
	v_fma_f32 v66, -v51, v53, 1.0
	v_fmac_f32_e32 v53, v66, v53
	v_div_scale_f32 v66, vcc, v30, v64, v30
	v_mul_f32_e32 v67, v66, v53
	v_fma_f32 v70, -v51, v67, v66
	v_fmac_f32_e32 v67, v70, v53
	v_fma_f32 v51, -v51, v67, v66
	v_div_fmas_f32 v51, v51, v53, v67
	v_div_fixup_f32 v64, v51, v64, v30
	v_cvt_f32_f16_sdwa v51, v233 dst_sel:DWORD dst_unused:UNUSED_PAD src0_sel:WORD_1
	v_cvt_f32_f16_e32 v53, v233
	v_pk_mul_f32 v[22:23], v[22:23], v[64:65]
	v_mul_f32_e32 v31, 0xbfb8aa3b, v51
	v_mul_f32_e32 v30, 0xbfb8aa3b, v53
	v_exp_f32_e32 v30, v30
	v_exp_f32_e32 v31, v31
	v_cvt_pk_f16_f32 v64, v22, v23
	v_pk_add_f32 v[30:31], v[30:31], 1.0 op_sel_hi:[1,0]
	s_nop 0
	v_div_scale_f32 v65, s[4:5], v31, v31, v51
	v_rcp_f32_e32 v66, v65
	s_nop 0
	v_fma_f32 v67, -v65, v66, 1.0
	v_fmac_f32_e32 v66, v67, v66
	v_div_scale_f32 v67, vcc, v51, v31, v51
	v_mul_f32_e32 v68, v67, v66
	v_fma_f32 v69, -v65, v68, v67
	v_fmac_f32_e32 v68, v69, v66
	v_fma_f32 v65, -v65, v68, v67
	v_div_fmas_f32 v65, v65, v66, v68
	v_div_fixup_f32 v31, v65, v31, v51
	v_div_scale_f32 v51, s[4:5], v30, v30, v53
	v_rcp_f32_e32 v65, v51
	s_nop 0
	v_fma_f32 v66, -v51, v65, 1.0
	v_fmac_f32_e32 v65, v66, v65
	v_div_scale_f32 v66, vcc, v53, v30, v53
	v_mul_f32_e32 v67, v66, v65
	v_fma_f32 v68, -v51, v67, v66
	v_fmac_f32_e32 v67, v68, v65
	v_fma_f32 v51, -v51, v67, v66
	v_div_fmas_f32 v51, v51, v65, v67
	v_div_fixup_f32 v30, v51, v30, v53
	v_pk_mul_f32 v[30:31], v[62:63], v[30:31]
	s_nop 0
	v_cvt_pk_f16_f32 v65, v30, v31
	ds_write2_b64 v49, v[2:3], v[64:65] offset0:64 offset1:68
	v_lshl_add_u64 v[2:3], v[44:45], 0, v[20:21]
	s_nop 0
	s_waitcnt vmcnt(3)
	v_cvt_f32_f16_sdwa v51, v234 dst_sel:DWORD dst_unused:UNUSED_PAD src0_sel:WORD_1
	v_cvt_f32_f16_e32 v2, v234
	s_waitcnt vmcnt(2)
	v_pk_add_f32 v[20:21], v[60:61], v[200:201]
	v_pk_add_f32 v[58:59], v[58:59], v[202:203]
	v_mul_f32_e32 v53, 0xbfb8aa3b, v2
	v_exp_f32_e32 v60, v53
	v_mul_f32_e32 v53, 0xbfb8aa3b, v51
	v_exp_f32_e32 v61, v53
	s_nop 0
	v_pk_add_f32 v[60:61], v[60:61], 1.0 op_sel_hi:[1,0]
	s_nop 0
	v_div_scale_f32 v53, s[4:5], v61, v61, v51
	v_rcp_f32_e32 v62, v53
	s_nop 0
	v_fma_f32 v63, -v53, v62, 1.0
	v_fmac_f32_e32 v62, v63, v62
	v_div_scale_f32 v63, vcc, v51, v61, v51
	v_mul_f32_e32 v66, v63, v62
	v_fma_f32 v67, -v53, v66, v63
	v_fmac_f32_e32 v66, v67, v62
	v_fma_f32 v53, -v53, v66, v63
	v_div_fmas_f32 v53, v53, v62, v66
	v_div_fixup_f32 v61, v53, v61, v51
	v_div_scale_f32 v51, s[4:5], v60, v60, v2
	v_rcp_f32_e32 v53, v51
	s_nop 0
	v_fma_f32 v62, -v51, v53, 1.0
	v_fmac_f32_e32 v53, v62, v53
	v_div_scale_f32 v62, vcc, v2, v60, v2
	v_mul_f32_e32 v63, v62, v53
	v_fma_f32 v66, -v51, v63, v62
	v_fmac_f32_e32 v63, v66, v53
	v_fma_f32 v51, -v51, v63, v62
	v_div_fmas_f32 v51, v51, v53, v63
	v_div_fixup_f32 v60, v51, v60, v2
	v_pk_mul_f32 v[60:61], v[20:21], v[60:61]
	v_cvt_f32_f16_sdwa v21, v235 dst_sel:DWORD dst_unused:UNUSED_PAD src0_sel:WORD_1
	v_cvt_f32_f16_e32 v51, v235
	v_cvt_pk_f16_f32 v20, v60, v61
	v_mul_f32_e32 v3, 0xbfb8aa3b, v21
	v_mul_f32_e32 v2, 0xbfb8aa3b, v51
	v_exp_f32_e32 v2, v2
	v_exp_f32_e32 v3, v3
	s_nop 0
	v_pk_add_f32 v[2:3], v[2:3], 1.0 op_sel_hi:[1,0]
	s_nop 0
	v_div_scale_f32 v53, s[4:5], v3, v3, v21
	v_rcp_f32_e32 v62, v53
	s_nop 0
	v_fma_f32 v63, -v53, v62, 1.0
	v_fmac_f32_e32 v62, v63, v62
	v_div_scale_f32 v63, vcc, v21, v3, v21
	v_mul_f32_e32 v64, v63, v62
	v_fma_f32 v65, -v53, v64, v63
	v_fmac_f32_e32 v64, v65, v62
	v_fma_f32 v53, -v53, v64, v63
	v_div_fmas_f32 v53, v53, v62, v64
	v_div_fixup_f32 v3, v53, v3, v21
	v_div_scale_f32 v21, s[4:5], v2, v2, v51
	v_rcp_f32_e32 v53, v21
	s_nop 0
	v_fma_f32 v62, -v21, v53, 1.0
	v_fmac_f32_e32 v53, v62, v53
	v_div_scale_f32 v62, vcc, v51, v2, v51
	v_mul_f32_e32 v63, v62, v53
	v_fma_f32 v64, -v21, v63, v62
	v_fmac_f32_e32 v63, v64, v53
	v_fma_f32 v21, -v21, v63, v62
	v_div_fmas_f32 v21, v21, v53, v63
	v_div_fixup_f32 v2, v21, v2, v51
	v_pk_mul_f32 v[58:59], v[58:59], v[2:3]
	v_lshl_add_u64 v[2:3], v[44:45], 0, v[24:25]
	s_nop 0
	v_cvt_pk_f16_f32 v21, v58, v59
	s_waitcnt vmcnt(1)
	v_cvt_f32_f16_sdwa v51, v236 dst_sel:DWORD dst_unused:UNUSED_PAD src0_sel:WORD_1
	v_cvt_f32_f16_e32 v24, v236
	s_waitcnt vmcnt(0)
	v_pk_add_f32 v[0:1], v[56:57], v[204:205]
	v_pk_add_f32 v[2:3], v[54:55], v[206:207]
	v_mul_f32_e32 v53, 0xbfb8aa3b, v24
	v_exp_f32_e32 v56, v53
	v_mul_f32_e32 v53, 0xbfb8aa3b, v51
	v_exp_f32_e32 v57, v53
	s_nop 0
	v_pk_add_f32 v[56:57], v[56:57], 1.0 op_sel_hi:[1,0]
	s_nop 0
	v_div_scale_f32 v53, s[4:5], v57, v57, v51
	v_rcp_f32_e32 v62, v53
	s_nop 0
	v_fma_f32 v63, -v53, v62, 1.0
	v_fmac_f32_e32 v62, v63, v62
	v_div_scale_f32 v63, vcc, v51, v57, v51
	v_mul_f32_e32 v64, v63, v62
	v_fma_f32 v65, -v53, v64, v63
	v_fmac_f32_e32 v64, v65, v62
	v_fma_f32 v53, -v53, v64, v63
	v_div_fmas_f32 v53, v53, v62, v64
	v_div_fixup_f32 v57, v53, v57, v51
	v_div_scale_f32 v51, s[4:5], v56, v56, v24
	v_rcp_f32_e32 v53, v51
	s_nop 0
	v_fma_f32 v62, -v51, v53, 1.0
	v_fmac_f32_e32 v53, v62, v53
	v_div_scale_f32 v62, vcc, v24, v56, v24
	v_mul_f32_e32 v63, v62, v53
	v_fma_f32 v64, -v51, v63, v62
	v_fmac_f32_e32 v63, v64, v53
	v_fma_f32 v51, -v51, v63, v62
	v_div_fmas_f32 v51, v51, v53, v63
	v_div_fixup_f32 v56, v51, v56, v24
	v_cvt_f32_f16_sdwa v51, v237 dst_sel:DWORD dst_unused:UNUSED_PAD src0_sel:WORD_1
	v_cvt_f32_f16_e32 v25, v237
	v_pk_mul_f32 v[0:1], v[0:1], v[56:57]
	v_mul_f32_e32 v53, 0xbfb8aa3b, v25
	v_exp_f32_e32 v54, v53
	v_mul_f32_e32 v53, 0xbfb8aa3b, v51
	v_exp_f32_e32 v55, v53
	v_cvt_pk_f16_f32 v24, v0, v1
	v_pk_add_f32 v[54:55], v[54:55], 1.0 op_sel_hi:[1,0]
	s_nop 0
	v_div_scale_f32 v53, s[4:5], v55, v55, v51
	v_rcp_f32_e32 v56, v53
	s_nop 0
	v_fma_f32 v57, -v53, v56, 1.0
	v_fmac_f32_e32 v56, v57, v56
	v_div_scale_f32 v57, vcc, v51, v55, v51
	v_mul_f32_e32 v62, v57, v56
	v_fma_f32 v63, -v53, v62, v57
	v_fmac_f32_e32 v62, v63, v56
	v_fma_f32 v53, -v53, v62, v57
	v_div_fmas_f32 v53, v53, v56, v62
	v_div_fixup_f32 v55, v53, v55, v51
	v_div_scale_f32 v51, s[4:5], v54, v54, v25
	v_rcp_f32_e32 v53, v51
	s_mov_b64 s[4:5], 0
	v_fma_f32 v56, -v51, v53, 1.0
	v_fmac_f32_e32 v53, v56, v53
	v_div_scale_f32 v56, vcc, v25, v54, v25
	v_mul_f32_e32 v57, v56, v53
	v_fma_f32 v62, -v51, v57, v56
	v_fmac_f32_e32 v57, v62, v53
	v_fma_f32 v51, -v51, v57, v56
	v_div_fmas_f32 v51, v51, v53, v57
	v_div_fixup_f32 v54, v51, v54, v25
	v_pk_mul_f32 v[2:3], v[2:3], v[54:55]
	v_mov_b32_e32 v55, v4
	v_mov_b32_e32 v4, v27
	v_mov_b32_e32 v54, v26
	v_pk_mul_f32 v[4:5], v[4:5], v[4:5]
	v_mov_b32_e32 v26, v28
	v_pk_fma_f32 v[4:5], v[54:55], v[54:55], v[4:5]
	v_mov_b32_e32 v27, v6
	v_mov_b32_e32 v6, v29
	v_pk_fma_f32 v[4:5], v[26:27], v[26:27], v[4:5]
	v_cvt_pk_f16_f32 v25, v2, v3
	v_pk_fma_f32 v[4:5], v[6:7], v[6:7], v[4:5]
	v_mov_b32_e32 v7, v8
	v_mov_b32_e32 v8, v23
	v_mov_b32_e32 v6, v22
	v_pk_mul_f32 v[8:9], v[8:9], v[8:9]
	v_pk_add_f32 v[4:5], v[36:37], v[4:5]
	v_pk_fma_f32 v[6:7], v[6:7], v[6:7], v[8:9]
	v_mov_b32_e32 v8, v30
	v_mov_b32_e32 v9, v10
	v_mov_b32_e32 v10, v31
	v_pk_fma_f32 v[6:7], v[8:9], v[8:9], v[6:7]
	s_and_b64 vcc, exec, s[36:37]
	v_pk_fma_f32 v[6:7], v[10:11], v[10:11], v[6:7]
	ds_write2_b64 v49, v[20:21], v[24:25] offset0:72 offset1:76
	v_pk_add_f32 v[4:5], v[4:5], v[6:7]
	v_mov_b32_e32 v7, v12
	v_mov_b32_e32 v12, v61
	v_mov_b32_e32 v6, v60
	v_pk_mul_f32 v[8:9], v[12:13], v[12:13]
	s_nop 0
	v_pk_fma_f32 v[6:7], v[6:7], v[6:7], v[8:9]
	v_mov_b32_e32 v8, v58
	v_mov_b32_e32 v9, v14
	v_mov_b32_e32 v14, v59
	v_pk_fma_f32 v[6:7], v[8:9], v[8:9], v[6:7]
	s_nop 0
	v_pk_fma_f32 v[6:7], v[14:15], v[14:15], v[6:7]
	s_nop 0
	v_pk_add_f32 v[4:5], v[4:5], v[6:7]
	v_mov_b32_e32 v7, v16
	v_mov_b32_e32 v16, v1
	v_mov_b32_e32 v6, v0
	v_pk_mul_f32 v[0:1], v[16:17], v[16:17]
	s_nop 0
	v_pk_fma_f32 v[0:1], v[6:7], v[6:7], v[0:1]
	v_mov_b32_e32 v6, v2
	v_mov_b32_e32 v7, v18
	v_mov_b32_e32 v18, v3
	v_pk_fma_f32 v[0:1], v[6:7], v[6:7], v[0:1]
	s_nop 0
	v_pk_fma_f32 v[0:1], v[18:19], v[18:19], v[0:1]
	s_nop 0
	v_pk_add_f32 v[36:37], v[4:5], v[0:1]
	s_cbranch_vccz .LBB0_103
	v_mbcnt_hi_u32_b32 v0, -1, v214
	v_and_b32_e32 v2, 64, v0
	v_xor_b32_e32 v1, 16, v0
	v_add_u32_e32 v3, 64, v2
	v_cmp_lt_i32_e32 vcc, v1, v3
	s_nop 1
	v_cndmask_b32_e32 v1, v0, v1, vcc
	v_lshlrev_b32_e32 v2, 2, v1
	ds_bpermute_b32 v4, v2, v37
	v_xor_b32_e32 v1, 32, v0
	v_cmp_lt_i32_e32 vcc, v1, v3
	s_waitcnt lgkmcnt(0)
	v_add_f32_e32 v4, v37, v4
	v_cndmask_b32_e32 v0, v0, v1, vcc
	v_lshlrev_b32_e32 v3, 2, v0
	ds_bpermute_b32 v5, v3, v4
	v_lshlrev_b32_e32 v0, 7, v95
	v_cmp_eq_u32_e32 vcc, 0, v96
	v_lshl_or_b32 v1, v94, 2, v0
	s_and_saveexec_b64 s[4:5], vcc
	s_cbranch_execz .LBB0_108
	s_waitcnt lgkmcnt(0)
	v_add_f32_e32 v4, v4, v5
	ds_write_b32 v1, v4 offset:52224
